# hand-written ml_k2 (swapped-operand MFMAs, 8-byte stores, pipelined LDS reads, L2 touch prefetch 2 chunks ahead) started 20us into the scan phase
# speedup vs baseline: 1.0119x; 1.0119x over previous
.LBB0_462:
	s_andn2_b64 vcc, exec, s[0:1]
	s_cbranch_vccnz .LBB0_474
	s_cmp_gt_i32 s52, 63
	s_mov_b64 s[0:1], -1
	s_cbranch_scc0 .LBB0_470
	s_and_b32 s44, s52, 3
	s_sub_u32 s47, s52, 64
	s_lshr_b32 s45, s47, 2
	v_and_b32_e32 v120, 63, v144
	v_lshrrev_b32_e32 v121, 6, v144
	v_and_b32_e32 v142, 15, v120
	v_lshrrev_b32_e32 v143, 4, v120
	v_lshlrev_b32_e32 v244, 2, v120
	s_movk_i32 s47, 144
	v_mul_u32_u24_e32 v249, s47, v120
	v_mul_u32_u24_e32 v246, s47, v142
	v_lshl_add_u32 v247, v143, 4, v246
	v_lshl_add_u32 v246, v143, 3, v246
	s_movk_i32 s47, 2304
	v_mad_u32_u24 v248, v121, s47, v247
	v_lshlrev_b32_e32 v250, 10, v121
	v_add_u32_e32 v250, 0x9000, v250
	v_add_u32_e32 v251, v250, v244
	v_lshl_add_u32 v253, v120, 3, v250
	v_add_u32_e32 v253, 256, v253
	v_lshl_add_u32 v252, v142, 3, v250
	v_add_u32_e32 v252, 256, v252
	v_lshlrev_b32_e32 v254, 13, v142
	v_lshl_add_u32 v254, v121, 5, v254
	v_lshl_add_u32 v254, v143, 3, v254
	v_lshrrev_b32_e32 v120, 3, v144
	v_and_b32_e32 v121, 7, v144
	v_lshlrev_b32_e32 v121, 4, v121
	v_lshl_add_u32 v236, v120, 13, v121
	v_add_u32_e32 v237, 0x40000, v236
	s_movk_i32 s47, 144
	v_mad_u32_u24 v245, v120, s47, v121
	v_lshlrev_b32_e32 v242, 4, v144
	v_add_u32_e32 v243, 4096, v242
	s_lshl_b32 s47, s45, 24
	s_lshl_b32 s48, s44, 7
	s_add_u32 s47, s47, s48
	s_add_u32 s48, s47, 0x3c41610
	s_add_u32 s4, s26, s48
	s_addc_u32 s5, s27, 0
	s_add_u32 s48, s47, 0x3c40a00
	s_add_u32 s42, s26, s48
	s_addc_u32 s43, s27, 0
	s_lshl_b32 s47, s45, 2
	s_add_u32 s47, s47, s44
	s_lshl_b32 s47, s47, 5
	s_mul_i32 s48, s47, 0x6000
	s_add_u32 s48, s48, 0x1800000
	s_add_u32 s6, s24, s48
	s_addc_u32 s7, s25, 0
	s_add_u32 s8, s6, 0x2000
	s_addc_u32 s9, s7, 0
	s_add_u32 s38, s6, 0x4000
	s_addc_u32 s39, s7, 0
	s_mul_i32 s48, s47, 0x500
	s_add_u32 s48, s48, 0x3000000
	s_add_u32 s40, s24, s48
	s_addc_u32 s41, s25, 0
	v_lshlrev_b32_e32 v120, 7, v144
	v_mov_b32_e32 v188, s6
	v_mov_b32_e32 v189, s7
	v_add_co_u32_e32 v188, vcc, v188, v120
	v_addc_co_u32_e32 v189, vcc, 0, v189, vcc
	v_mov_b32_e32 v192, 0x6000
	v_mov_b32_e32 v193, 0
	v_subrev_u32_e32 v121, 192, v144
	v_lshlrev_b32_e32 v121, 13, v121
	v_mov_b32_e32 v142, s4
	v_mov_b32_e32 v143, s5
	v_add_co_u32_e32 v142, vcc, v142, v121
	v_addc_co_u32_e32 v143, vcc, 0, v143, vcc
	v_cmp_lt_u32_e32 vcc, 191, v144
	s_nop 1
	v_cndmask_b32_e32 v188, v188, v142, vcc
	v_cndmask_b32_e32 v189, v189, v143, vcc
	v_mov_b32_e32 v121, 0x80000
	v_cndmask_b32_e32 v192, v192, v121, vcc
	v_mov_b32_e32 v190, v188
	v_mov_b32_e32 v191, v189
	v_mov_b32_e32 v194, v192
	v_mov_b32_e32 v195, 0
	v_subrev_u32_e32 v120, 64, v144
	v_lshlrev_b32_e32 v120, 7, v120
	v_mov_b32_e32 v142, s40
	v_mov_b32_e32 v143, s41
	v_add_co_u32_e32 v142, vcc, v142, v120
	v_addc_co_u32_e32 v143, vcc, 0, v143, vcc
	v_subrev_u32_e32 v120, 64, v144
	v_cmp_gt_u32_e32 vcc, 10, v120
	s_nop 1
	v_cndmask_b32_e32 v190, v190, v142, vcc
	v_cndmask_b32_e32 v191, v191, v143, vcc
	v_mov_b32_e32 v121, 0x500
	v_cndmask_b32_e32 v194, v194, v121, vcc
	v_lshlrev_b32_e32 v120, 13, v144
	v_add_u32_e32 v120, 128, v120
	v_mov_b32_e32 v142, s4
	v_mov_b32_e32 v143, s5
	v_add_co_u32_e32 v142, vcc, v142, v120
	v_addc_co_u32_e32 v143, vcc, 0, v143, vcc
	v_cmp_gt_u32_e32 vcc, 64, v144
	s_nop 1
	v_cndmask_b32_e32 v190, v190, v142, vcc
	v_cndmask_b32_e32 v191, v191, v143, vcc
	v_mov_b32_e32 v121, 0x80000
	v_cndmask_b32_e32 v194, v194, v121, vcc
	v_lshl_add_u64 v[188:189], v[188:189], 0, v[192:193]
	v_lshl_add_u64 v[190:191], v[190:191], 0, v[194:195]
	s_barrier
	global_load_dwordx4 v[66:69], v236, s[4:5]
	global_load_dwordx4 v[74:77], v242, s[6:7]
	global_load_dwordx4 v[82:85], v242, s[8:9]
	global_load_dwordx4 v[90:93], v242, s[38:39]
	global_load_dwordx4 v[70:73], v237, s[4:5]
	global_load_dwordx4 v[78:81], v243, s[6:7]
	global_load_dwordx4 v[86:89], v243, s[8:9]
	global_load_dwordx4 v[94:97], v243, s[38:39]
	global_load_dword v98, v244, s[40:41]
	global_load_dword v99, v244, s[40:41] offset:256
	global_load_dword v100, v244, s[40:41] offset:512
	global_load_dword v101, v244, s[40:41] offset:768
	global_load_dword v102, v1, s[40:41] offset:1024
	global_load_dword v103, v1, s[40:41] offset:252
	s_add_u32 s4, s4, 0x80000
	s_addc_u32 s5, s5, 0
	s_add_u32 s6, s6, 0x6000
	s_addc_u32 s7, s7, 0
	s_add_u32 s8, s8, 0x6000
	s_addc_u32 s9, s9, 0
	s_add_u32 s38, s38, 0x6000
	s_addc_u32 s39, s39, 0
	s_add_u32 s40, s40, 0x500
	s_addc_u32 s41, s41, 0
	global_load_ubyte v125, v[188:189], off
	global_load_ubyte v125, v[190:191], off
	v_lshl_add_u64 v[188:189], v[188:189], 0, v[192:193]
	v_lshl_add_u64 v[190:191], v[190:191], 0, v[194:195]
	v_mov_b32_e32 v2, 0
	v_mov_b32_e32 v3, 0
	v_mov_b32_e32 v4, 0
	v_mov_b32_e32 v5, 0
	v_mov_b32_e32 v6, 0
	v_mov_b32_e32 v7, 0
	v_mov_b32_e32 v8, 0
	v_mov_b32_e32 v9, 0
	v_mov_b32_e32 v10, 0
	v_mov_b32_e32 v11, 0
	v_mov_b32_e32 v12, 0
	v_mov_b32_e32 v13, 0
	v_mov_b32_e32 v14, 0
	v_mov_b32_e32 v15, 0
	v_mov_b32_e32 v16, 0
	v_mov_b32_e32 v17, 0
	v_mov_b32_e32 v118, 0
	v_mov_b32_e32 v119, 0
	s_mov_b32 s2, 0
	s_waitcnt vmcnt(2)
	s_movk_i32 s47, 5
.Lmk2_slp:
	s_sleep 127
	s_sub_u32 s47, s47, 1
	s_cmp_lg_u32 s47, 0
	s_cbranch_scc1 .Lmk2_slp
.Lmk2_chunk:
	s_waitcnt vmcnt(6)
	ds_write_b128 v245, v[66:69]
	ds_write_b128 v245, v[74:77] offset:9216
	ds_write_b128 v245, v[82:85] offset:18432
	ds_write_b128 v245, v[90:93] offset:27648
	ds_write_b128 v245, v[70:73] offset:4608
	ds_write_b128 v245, v[78:81] offset:13824
	ds_write_b128 v245, v[86:89] offset:23040
	ds_write_b128 v245, v[94:97] offset:32256
	ds_write_b32 v251, v118
	v_mov_b32_e32 v104, v98
	v_mov_b32_e32 v105, v99
	v_mov_b32_e32 v106, v100
	v_mov_b32_e32 v107, v101
	v_mov_b32_e32 v108, v102
	v_mov_b32_e32 v109, v103
	v_cvt_pk_bf16_f32 v228, v2, v3
	v_cvt_pk_bf16_f32 v229, v4, v5
	v_cvt_pk_bf16_f32 v230, v6, v7
	v_cvt_pk_bf16_f32 v231, v8, v9
	v_cvt_pk_bf16_f32 v232, v10, v11
	v_cvt_pk_bf16_f32 v233, v12, v13
	v_cvt_pk_bf16_f32 v234, v14, v15
	v_cvt_pk_bf16_f32 v235, v16, v17
	v_max_f32_e32 v138, v119, v105
	v_sub_f32_e32 v139, v119, v138
	v_mul_f32_e32 v139, 0x3fb8aa3b, v139
	v_exp_f32_e32 v139, v139
	v_sub_f32_e32 v140, v108, v138
	v_mul_f32_e32 v140, 0x3fb8aa3b, v140
	v_exp_f32_e32 v140, v140
	v_add_f32_e32 v141, v138, v104
	v_mul_f32_e32 v141, 0xbfb8aa3b, v141
	v_exp_f32_e32 v141, v141
	v_max_f32_e32 v0, v119, v108
	v_sub_f32_e32 v186, v119, v0
	v_mul_f32_e32 v186, 0x3fb8aa3b, v186
	v_exp_f32_e32 v186, v186
	v_sub_f32_e32 v184, v108, v0
	v_mul_f32_e32 v184, 0x3fb8aa3b, v184
	v_exp_f32_e32 v184, v184
	v_add_f32_e32 v119, v109, v0
	s_waitcnt lgkmcnt(0)
	s_barrier
	ds_read_b64 v[196:197], v246 offset:0
	ds_read_b64 v[198:199], v246 offset:32
	ds_read_b128 v[126:129], v249 offset:0
	ds_read_b128 v[164:167], v250 offset:0
	ds_read_b128 v[168:171], v250 offset:16
	ds_read_b64 v[200:201], v246 offset:2304
	ds_read_b64 v[202:203], v246 offset:2336
	ds_read_b64 v[204:205], v246 offset:4608
	ds_read_b64 v[206:207], v246 offset:4640
	ds_read_b64 v[208:209], v246 offset:6912
	ds_read_b64 v[210:211], v246 offset:6944
	s_waitcnt lgkmcnt(9)
	v_mfma_f32_16x16x32_bf16 v[18:21], v[228:231], v[196:199], 0
	global_load_dwordx4 v[66:69], v236, s[4:5]
	ds_read_b128 v[130:133], v249 offset:16
	ds_read_b128 v[172:175], v250 offset:32
	ds_read_b128 v[176:179], v250 offset:48
	s_waitcnt lgkmcnt(9)
	v_and_b32_e32 v120, 0xffff0000, v126
	v_mul_f32_e32 v142, v165, v120
	v_lshlrev_b32_e32 v121, 16, v126
	v_fmac_f32_e32 v142, v164, v121
	v_lshlrev_b32_e32 v120, 16, v127
	v_fmac_f32_e32 v142, v166, v120
	v_and_b32_e32 v121, 0xffff0000, v127
	v_fmac_f32_e32 v142, v167, v121
	v_lshlrev_b32_e32 v120, 16, v128
	v_fmac_f32_e32 v142, v168, v120
	v_and_b32_e32 v121, 0xffff0000, v128
	v_fmac_f32_e32 v142, v169, v121
	v_lshlrev_b32_e32 v120, 16, v129
	v_fmac_f32_e32 v142, v170, v120
	v_and_b32_e32 v121, 0xffff0000, v129
	v_fmac_f32_e32 v142, v171, v121
	v_add_f32_e32 v143, 0, v142
	ds_read_b64 v[212:213], v246 offset:64
	ds_read_b64 v[214:215], v246 offset:96
	s_waitcnt lgkmcnt(9)
	v_mfma_f32_16x16x32_bf16 v[22:25], v[228:231], v[200:203], 0
	global_load_dwordx4 v[74:77], v242, s[6:7]
	ds_read_b64 v[216:217], v246 offset:2368
	ds_read_b64 v[218:219], v246 offset:2400
	s_waitcnt lgkmcnt(9)
	v_mfma_f32_16x16x32_bf16 v[26:29], v[228:231], v[204:207], 0
	global_load_dwordx4 v[82:85], v242, s[8:9]
	ds_read_b64 v[220:221], v246 offset:4672
	ds_read_b64 v[222:223], v246 offset:4704
	s_waitcnt lgkmcnt(9)
	v_mfma_f32_16x16x32_bf16 v[30:33], v[228:231], v[208:211], 0
	global_load_dwordx4 v[90:93], v242, s[38:39]
	ds_read_b128 v[134:137], v249 offset:32
	ds_read_b128 v[164:167], v250 offset:64
	ds_read_b128 v[168:171], v250 offset:80
	s_waitcnt lgkmcnt(9)
	v_and_b32_e32 v120, 0xffff0000, v130
	v_mul_f32_e32 v142, v173, v120
	v_lshlrev_b32_e32 v121, 16, v130
	v_fmac_f32_e32 v142, v172, v121
	v_lshlrev_b32_e32 v120, 16, v131
	v_fmac_f32_e32 v142, v174, v120
	v_and_b32_e32 v121, 0xffff0000, v131
	v_fmac_f32_e32 v142, v175, v121
	v_lshlrev_b32_e32 v120, 16, v132
	v_fmac_f32_e32 v142, v176, v120
	v_and_b32_e32 v121, 0xffff0000, v132
	v_fmac_f32_e32 v142, v177, v121
	v_lshlrev_b32_e32 v120, 16, v133
	v_fmac_f32_e32 v142, v178, v120
	v_and_b32_e32 v121, 0xffff0000, v133
	v_fmac_f32_e32 v142, v179, v121
	v_add_f32_e32 v143, v143, v142
	ds_read_b64 v[224:225], v246 offset:6976
	ds_read_b64 v[226:227], v246 offset:7008
	s_waitcnt lgkmcnt(9)
	v_mfma_f32_16x16x32_bf16 v[18:21], v[232:235], v[212:215], v[18:21]
	global_load_dwordx4 v[70:73], v237, s[4:5]
	ds_read_b128 v[110:113], v248 offset:27648
	ds_read_b128 v[196:199], v247 offset:9216
	s_waitcnt lgkmcnt(9)
	v_mfma_f32_16x16x32_bf16 v[22:25], v[232:235], v[216:219], v[22:25]
	global_load_dwordx4 v[78:81], v243, s[6:7]
	ds_read_b128 v[200:203], v247 offset:11520
	s_waitcnt lgkmcnt(8)
	v_mfma_f32_16x16x32_bf16 v[26:29], v[232:235], v[220:223], v[26:29]
	global_load_dwordx4 v[86:89], v243, s[8:9]
	ds_read_b128 v[126:129], v249 offset:48
	ds_read_b128 v[172:175], v250 offset:96
	ds_read_b128 v[176:179], v250 offset:112
	s_waitcnt lgkmcnt(8)
	v_and_b32_e32 v120, 0xffff0000, v134
	v_mul_f32_e32 v142, v165, v120
	v_lshlrev_b32_e32 v121, 16, v134
	v_fmac_f32_e32 v142, v164, v121
	v_lshlrev_b32_e32 v120, 16, v135
	v_fmac_f32_e32 v142, v166, v120
	v_and_b32_e32 v121, 0xffff0000, v135
	v_fmac_f32_e32 v142, v167, v121
	v_lshlrev_b32_e32 v120, 16, v136
	v_fmac_f32_e32 v142, v168, v120
	v_and_b32_e32 v121, 0xffff0000, v136
	v_fmac_f32_e32 v142, v169, v121
	v_lshlrev_b32_e32 v120, 16, v137
	v_fmac_f32_e32 v142, v170, v120
	v_and_b32_e32 v121, 0xffff0000, v137
	v_fmac_f32_e32 v142, v171, v121
	v_add_f32_e32 v143, v143, v142
	ds_read_b128 v[204:207], v247 offset:13824
	s_waitcnt lgkmcnt(7)
	v_mfma_f32_16x16x32_bf16 v[30:33], v[232:235], v[224:227], v[30:33]
	global_load_dwordx4 v[94:97], v243, s[38:39]
	ds_read_b128 v[208:211], v247 offset:16128
	s_waitcnt lgkmcnt(6)
	v_mfma_f32_16x16x32_bf16 v[34:37], v[110:113], v[196:199], 0
	global_load_dword v98, v244, s[40:41]
	ds_read_b128 v[114:117], v248 offset:27712
	ds_read_b128 v[212:215], v247 offset:9280
	s_waitcnt lgkmcnt(7)
	v_mfma_f32_16x16x32_bf16 v[38:41], v[110:113], v[200:203], 0
	global_load_dword v99, v244, s[40:41] offset:256
	ds_read_b128 v[130:133], v249 offset:64
	ds_read_b128 v[164:167], v250 offset:128
	ds_read_b128 v[168:171], v250 offset:144
	s_waitcnt lgkmcnt(7)
	v_and_b32_e32 v120, 0xffff0000, v126
	v_mul_f32_e32 v142, v173, v120
	v_lshlrev_b32_e32 v121, 16, v126
	v_fmac_f32_e32 v142, v172, v121
	v_lshlrev_b32_e32 v120, 16, v127
	v_fmac_f32_e32 v142, v174, v120
	v_and_b32_e32 v121, 0xffff0000, v127
	v_fmac_f32_e32 v142, v175, v121
	v_lshlrev_b32_e32 v120, 16, v128
	v_fmac_f32_e32 v142, v176, v120
	v_and_b32_e32 v121, 0xffff0000, v128
	v_fmac_f32_e32 v142, v177, v121
	v_lshlrev_b32_e32 v120, 16, v129
	v_fmac_f32_e32 v142, v178, v120
	v_and_b32_e32 v121, 0xffff0000, v129
	v_fmac_f32_e32 v142, v179, v121
	v_add_f32_e32 v143, v143, v142
	ds_read_b128 v[216:219], v247 offset:11584
	s_waitcnt lgkmcnt(7)
	v_mfma_f32_16x16x32_bf16 v[42:45], v[110:113], v[204:207], 0
	global_load_dword v100, v244, s[40:41] offset:512
	ds_read_b128 v[220:223], v247 offset:13888
	s_waitcnt lgkmcnt(7)
	v_mfma_f32_16x16x32_bf16 v[46:49], v[110:113], v[208:211], 0
	global_load_dword v101, v244, s[40:41] offset:768
	ds_read_b128 v[224:227], v247 offset:16192
	s_waitcnt lgkmcnt(6)
	v_mfma_f32_16x16x32_bf16 v[34:37], v[114:117], v[212:215], v[34:37]
	global_load_dword v102, v1, s[40:41] offset:1024
	ds_read_b128 v[134:137], v249 offset:80
	ds_read_b128 v[172:175], v250 offset:160
	ds_read_b128 v[176:179], v250 offset:176
	s_waitcnt lgkmcnt(6)
	v_and_b32_e32 v120, 0xffff0000, v130
	v_mul_f32_e32 v142, v165, v120
	v_lshlrev_b32_e32 v121, 16, v130
	v_fmac_f32_e32 v142, v164, v121
	v_lshlrev_b32_e32 v120, 16, v131
	v_fmac_f32_e32 v142, v166, v120
	v_and_b32_e32 v121, 0xffff0000, v131
	v_fmac_f32_e32 v142, v167, v121
	v_lshlrev_b32_e32 v120, 16, v132
	v_fmac_f32_e32 v142, v168, v120
	v_and_b32_e32 v121, 0xffff0000, v132
	v_fmac_f32_e32 v142, v169, v121
	v_lshlrev_b32_e32 v120, 16, v133
	v_fmac_f32_e32 v142, v170, v120
	v_and_b32_e32 v121, 0xffff0000, v133
	v_fmac_f32_e32 v142, v171, v121
	v_add_f32_e32 v143, v143, v142
	ds_read_b128 v[196:199], v247 offset:18432
	s_waitcnt lgkmcnt(6)
	v_mfma_f32_16x16x32_bf16 v[38:41], v[114:117], v[216:219], v[38:41]
	global_load_dword v103, v1, s[40:41] offset:252
	s_cmpk_lt_u32 s2, 30
	s_cselect_b32 s47, 0x80000, 0
	s_add_u32 s4, s4, s47
	s_addc_u32 s5, s5, 0
	s_cmpk_lt_u32 s2, 30
	s_cselect_b32 s47, 0x6000, 0
	s_cselect_b32 s48, 0x500, 0
	s_add_u32 s6, s6, s47
	s_addc_u32 s7, s7, 0
	s_add_u32 s8, s8, s47
	s_addc_u32 s9, s9, 0
	s_add_u32 s38, s38, s47
	s_addc_u32 s39, s39, 0
	s_add_u32 s40, s40, s48
	s_addc_u32 s41, s41, 0
	global_load_ubyte v125, v[188:189], off
	global_load_ubyte v125, v[190:191], off
	v_lshl_add_u64 v[188:189], v[188:189], 0, v[192:193]
	v_lshl_add_u64 v[190:191], v[190:191], 0, v[194:195]
	ds_read_b128 v[200:203], v247 offset:20736
	s_waitcnt lgkmcnt(6)
	v_mfma_f32_16x16x32_bf16 v[42:45], v[114:117], v[220:223], v[42:45]
	ds_read_b128 v[204:207], v247 offset:23040
	s_waitcnt lgkmcnt(6)
	v_mfma_f32_16x16x32_bf16 v[46:49], v[114:117], v[224:227], v[46:49]
	ds_read_b128 v[126:129], v249 offset:96
	ds_read_b128 v[164:167], v250 offset:192
	ds_read_b128 v[168:171], v250 offset:208
	s_waitcnt lgkmcnt(6)
	v_and_b32_e32 v120, 0xffff0000, v134
	v_mul_f32_e32 v142, v173, v120
	v_lshlrev_b32_e32 v121, 16, v134
	v_fmac_f32_e32 v142, v172, v121
	v_lshlrev_b32_e32 v120, 16, v135
	v_fmac_f32_e32 v142, v174, v120
	v_and_b32_e32 v121, 0xffff0000, v135
	v_fmac_f32_e32 v142, v175, v121
	v_lshlrev_b32_e32 v120, 16, v136
	v_fmac_f32_e32 v142, v176, v120
	v_and_b32_e32 v121, 0xffff0000, v136
	v_fmac_f32_e32 v142, v177, v121
	v_lshlrev_b32_e32 v120, 16, v137
	v_fmac_f32_e32 v142, v178, v120
	v_and_b32_e32 v121, 0xffff0000, v137
	v_fmac_f32_e32 v142, v179, v121
	v_add_f32_e32 v143, v143, v142
	ds_read_b128 v[208:211], v247 offset:25344
	s_waitcnt lgkmcnt(6)
	v_mfma_f32_16x16x32_bf16 v[50:53], v[196:199], v[110:113], 0
	ds_read_b128 v[212:215], v247 offset:18496
	s_waitcnt lgkmcnt(6)
	v_mfma_f32_16x16x32_bf16 v[54:57], v[200:203], v[110:113], 0
	ds_read_b128 v[216:219], v247 offset:20800
	s_waitcnt lgkmcnt(6)
	v_mfma_f32_16x16x32_bf16 v[58:61], v[204:207], v[110:113], 0
	ds_read_b128 v[130:133], v249 offset:112
	ds_read_b128 v[172:175], v250 offset:224
	ds_read_b128 v[176:179], v250 offset:240
	s_waitcnt lgkmcnt(6)
	v_and_b32_e32 v120, 0xffff0000, v126
	v_mul_f32_e32 v142, v165, v120
	v_lshlrev_b32_e32 v121, 16, v126
	v_fmac_f32_e32 v142, v164, v121
	v_lshlrev_b32_e32 v120, 16, v127
	v_fmac_f32_e32 v142, v166, v120
	v_and_b32_e32 v121, 0xffff0000, v127
	v_fmac_f32_e32 v142, v167, v121
	v_lshlrev_b32_e32 v120, 16, v128
	v_fmac_f32_e32 v142, v168, v120
	v_and_b32_e32 v121, 0xffff0000, v128
	v_fmac_f32_e32 v142, v169, v121
	v_lshlrev_b32_e32 v120, 16, v129
	v_fmac_f32_e32 v142, v170, v120
	v_and_b32_e32 v121, 0xffff0000, v129
	v_fmac_f32_e32 v142, v171, v121
	v_add_f32_e32 v143, v143, v142
	ds_read_b128 v[220:223], v247 offset:23104
	s_waitcnt lgkmcnt(6)
	v_mfma_f32_16x16x32_bf16 v[62:65], v[208:211], v[110:113], 0
	ds_read_b128 v[224:227], v247 offset:25408
	s_waitcnt lgkmcnt(6)
	v_mfma_f32_16x16x32_bf16 v[50:53], v[212:215], v[114:117], v[50:53]
	s_waitcnt lgkmcnt(5)
	v_mfma_f32_16x16x32_bf16 v[54:57], v[216:219], v[114:117], v[54:57]
	s_waitcnt lgkmcnt(2)
	v_and_b32_e32 v120, 0xffff0000, v130
	v_mul_f32_e32 v142, v173, v120
	v_lshlrev_b32_e32 v121, 16, v130
	v_fmac_f32_e32 v142, v172, v121
	v_lshlrev_b32_e32 v120, 16, v131
	v_fmac_f32_e32 v142, v174, v120
	v_and_b32_e32 v121, 0xffff0000, v131
	v_fmac_f32_e32 v142, v175, v121
	v_lshlrev_b32_e32 v120, 16, v132
	v_fmac_f32_e32 v142, v176, v120
	v_and_b32_e32 v121, 0xffff0000, v132
	v_fmac_f32_e32 v142, v177, v121
	v_lshlrev_b32_e32 v120, 16, v133
	v_fmac_f32_e32 v142, v178, v120
	v_and_b32_e32 v121, 0xffff0000, v133
	v_fmac_f32_e32 v142, v179, v121
	v_add_f32_e32 v143, v143, v142
	s_waitcnt lgkmcnt(1)
	v_mfma_f32_16x16x32_bf16 v[58:61], v[220:223], v[114:117], v[58:61]
	s_waitcnt lgkmcnt(0)
	v_mfma_f32_16x16x32_bf16 v[62:65], v[224:227], v[114:117], v[62:65]
	v_mul_f32_e32 v143, v139, v143
	v_fmac_f32_e32 v143, v106, v140
	v_max_f32_e64 v143, |v143|, v141
	v_rcp_f32_e32 v143, v143
	s_nop 0
	v_mul_f32_e32 v120, v139, v143
	v_mul_f32_e32 v121, v140, v143
	ds_write_b64 v253, v[120:121]
	s_waitcnt lgkmcnt(0)
	ds_read_b64 v[164:165], v252 offset:0
	ds_read_b64 v[166:167], v252 offset:128
	ds_read_b64 v[168:169], v252 offset:256
	ds_read_b64 v[170:171], v252 offset:384
	s_waitcnt lgkmcnt(0)
	v_mul_f32_e32 v180, v34, v165
	v_fmac_f32_e32 v180, v18, v164
	v_mul_f32_e32 v181, v35, v165
	v_fmac_f32_e32 v181, v19, v164
	v_mul_f32_e32 v182, v36, v165
	v_fmac_f32_e32 v182, v20, v164
	v_mul_f32_e32 v183, v37, v165
	v_fmac_f32_e32 v183, v21, v164
	v_cvt_pk_bf16_f32 v172, v180, v181
	v_cvt_pk_bf16_f32 v173, v182, v183
	global_store_dwordx2 v254, v[172:173], s[42:43]
	v_mul_f32_e32 v180, v38, v167
	v_fmac_f32_e32 v180, v22, v166
	v_mul_f32_e32 v181, v39, v167
	v_fmac_f32_e32 v181, v23, v166
	v_mul_f32_e32 v182, v40, v167
	v_fmac_f32_e32 v182, v24, v166
	v_mul_f32_e32 v183, v41, v167
	v_fmac_f32_e32 v183, v25, v166
	v_cvt_pk_bf16_f32 v174, v180, v181
	v_cvt_pk_bf16_f32 v175, v182, v183
	v_add_u32_e32 v120, 0x20000, v254
	global_store_dwordx2 v120, v[174:175], s[42:43]
	v_mul_f32_e32 v180, v42, v169
	v_fmac_f32_e32 v180, v26, v168
	v_mul_f32_e32 v181, v43, v169
	v_fmac_f32_e32 v181, v27, v168
	v_mul_f32_e32 v182, v44, v169
	v_fmac_f32_e32 v182, v28, v168
	v_mul_f32_e32 v183, v45, v169
	v_fmac_f32_e32 v183, v29, v168
	v_cvt_pk_bf16_f32 v176, v180, v181
	v_cvt_pk_bf16_f32 v177, v182, v183
	v_add_u32_e32 v120, 0x40000, v254
	global_store_dwordx2 v120, v[176:177], s[42:43]
	v_mul_f32_e32 v180, v46, v171
	v_fmac_f32_e32 v180, v30, v170
	v_mul_f32_e32 v181, v47, v171
	v_fmac_f32_e32 v181, v31, v170
	v_mul_f32_e32 v182, v48, v171
	v_fmac_f32_e32 v182, v32, v170
	v_mul_f32_e32 v183, v49, v171
	v_fmac_f32_e32 v183, v33, v170
	v_cvt_pk_bf16_f32 v178, v180, v181
	v_cvt_pk_bf16_f32 v179, v182, v183
	v_add_u32_e32 v120, 0x60000, v254
	global_store_dwordx2 v120, v[178:179], s[42:43]
	s_add_u32 s42, s42, 0x80000
	s_addc_u32 s43, s43, 0
	v_pk_mul_f32 v[50:51], v[184:185], v[50:51] op_sel_hi:[0,1]
	v_pk_mul_f32 v[52:53], v[184:185], v[52:53] op_sel_hi:[0,1]
	v_pk_mul_f32 v[54:55], v[184:185], v[54:55] op_sel_hi:[0,1]
	v_pk_mul_f32 v[56:57], v[184:185], v[56:57] op_sel_hi:[0,1]
	v_pk_mul_f32 v[58:59], v[184:185], v[58:59] op_sel_hi:[0,1]
	v_pk_mul_f32 v[60:61], v[184:185], v[60:61] op_sel_hi:[0,1]
	v_pk_mul_f32 v[62:63], v[184:185], v[62:63] op_sel_hi:[0,1]
	v_pk_mul_f32 v[64:65], v[184:185], v[64:65] op_sel_hi:[0,1]
	v_pk_fma_f32 v[2:3], v[2:3], v[186:187], v[50:51] op_sel_hi:[1,0,1]
	v_pk_fma_f32 v[4:5], v[4:5], v[186:187], v[52:53] op_sel_hi:[1,0,1]
	v_pk_fma_f32 v[6:7], v[6:7], v[186:187], v[54:55] op_sel_hi:[1,0,1]
	v_pk_fma_f32 v[8:9], v[8:9], v[186:187], v[56:57] op_sel_hi:[1,0,1]
	v_pk_fma_f32 v[10:11], v[10:11], v[186:187], v[58:59] op_sel_hi:[1,0,1]
	v_pk_fma_f32 v[12:13], v[12:13], v[186:187], v[60:61] op_sel_hi:[1,0,1]
	v_pk_fma_f32 v[14:15], v[14:15], v[186:187], v[62:63] op_sel_hi:[1,0,1]
	v_pk_fma_f32 v[16:17], v[16:17], v[186:187], v[64:65] op_sel_hi:[1,0,1]
	v_mul_f32_e32 v120, v118, v186
	v_mul_f32_e32 v121, v107, v184
	v_add_f32_e32 v118, v120, v121
	s_barrier
	s_add_u32 s2, s2, 1
	s_cmpk_lt_u32 s2, 32
	s_cbranch_scc1 .Lmk2_chunk
.Lmk2_done:
	v_readlane_b32 s47, v239, 53
	s_lshl_b32 s47, s47, 3
	s_add_u32 s47, s47, s45
	s_lshl_b32 s47, s47, 2
	s_add_u32 s47, s47, s44
	s_lshl_b32 s48, s47, 14
	s_add_u32 s48, s48, 0x4850000
	s_add_u32 s42, s24, s48
	s_addc_u32 s43, s25, 0
	v_and_b32_e32 v120, 63, v144
	v_lshrrev_b32_e32 v121, 6, v144
	v_and_b32_e32 v142, 15, v120
	v_lshrrev_b32_e32 v143, 4, v120
	v_lshlrev_b32_e32 v142, 2, v142
	v_lshl_add_u32 v142, v121, 6, v142
	v_lshl_add_u32 v142, v143, 10, v142
	global_store_dword v142, v2, s[42:43] offset:0
	global_store_dword v142, v3, s[42:43] offset:256
	global_store_dword v142, v4, s[42:43] offset:512
	global_store_dword v142, v5, s[42:43] offset:768
	v_add_u32_e32 v142, 0x1000, v142
	global_store_dword v142, v6, s[42:43] offset:0
	global_store_dword v142, v7, s[42:43] offset:256
	global_store_dword v142, v8, s[42:43] offset:512
	global_store_dword v142, v9, s[42:43] offset:768
	v_add_u32_e32 v142, 0x1000, v142
	global_store_dword v142, v10, s[42:43] offset:0
	global_store_dword v142, v11, s[42:43] offset:256
	global_store_dword v142, v12, s[42:43] offset:512
	global_store_dword v142, v13, s[42:43] offset:768
	v_add_u32_e32 v142, 0x1000, v142
	global_store_dword v142, v14, s[42:43] offset:0
	global_store_dword v142, v15, s[42:43] offset:256
	global_store_dword v142, v16, s[42:43] offset:512
	global_store_dword v142, v17, s[42:43] offset:768
	s_lshl_b32 s48, s47, 8
	s_add_u32 s48, s48, 0x4950000
	s_add_u32 s42, s24, s48
	s_addc_u32 s43, s25, 0
	v_cmp_gt_u32_e32 vcc, 64, v144
	s_and_saveexec_b64 s[0:1], vcc
	global_store_dword v244, v118, s[42:43]
	s_lshl_b32 s48, s47, 2
	s_add_u32 s48, s48, 0x4954000
	s_add_u32 s42, s24, s48
	s_addc_u32 s43, s25, 0
	v_cmp_eq_u32_e32 vcc, 0, v144
	s_and_b64 exec, exec, vcc
	global_store_dword v1, v119, s[42:43]
	s_mov_b64 exec, s[0:1]
	s_waitcnt vmcnt(0)
	s_mov_b64 s[0:1], 0
